# post_rows: 33 of the 37 ds_bpermute lane exchanges (xor 1/2/4/8) replaced by DPP moves (bit-identical), padded to keep later code placement
# baseline (speedup 1.0000x reference)
.LBB0_253:
	s_or_b64 exec, exec, s[72:73]
	s_waitcnt vmcnt(7)
	v_and_b32_e32 v143, 0xffff0000, v120
	v_lshlrev_b32_e32 v141, 16, v120
	v_mul_f32_e32 v156, v143, v143
	v_lshlrev_b32_e32 v145, 16, v121
	v_fmac_f32_e32 v156, v141, v141
	v_and_b32_e32 v155, 0xffff0000, v121
	v_fmac_f32_e32 v156, v145, v145
	v_lshlrev_b32_e32 v158, 16, v122
	v_fmac_f32_e32 v156, v155, v155
	v_and_b32_e32 v159, 0xffff0000, v122
	v_fmac_f32_e32 v156, v158, v158
	v_lshlrev_b32_e32 v160, 16, v123
	v_fmac_f32_e32 v156, v159, v159
	v_and_b32_e32 v161, 0xffff0000, v123
	v_fmac_f32_e32 v156, v160, v160
	v_and_b32_e32 v120, 0xffff0000, v116
	v_lshlrev_b32_e32 v121, 16, v116
	v_fmac_f32_e32 v156, v161, v161
	v_pk_mul_f32 v[122:123], v[120:121], v[120:121]
	v_lshl_or_b32 v92, v95, 3, v148
	v_add_f32_e32 v116, v123, v156
	v_add_f32_e32 v156, v122, v116
	v_and_b32_e32 v116, 0xffff0000, v117
	v_lshlrev_b32_e32 v117, 16, v117
	v_pk_mul_f32 v[122:123], v[116:117], v[116:117]
	v_ashrrev_i32_e32 v93, 31, v92
	v_add_f32_e32 v123, v123, v156
	v_add_f32_e32 v162, v122, v123
	v_and_b32_e32 v122, 0xffff0000, v118
	v_lshlrev_b32_e32 v123, 16, v118
	v_pk_mul_f32 v[156:157], v[122:123], v[122:123]
	v_lshlrev_b64 v[96:97], 7, v[124:125]
	v_add_f32_e32 v118, v157, v162
	v_add_f32_e32 v162, v156, v118
	v_and_b32_e32 v118, 0xffff0000, v119
	v_lshlrev_b32_e32 v119, 16, v119
	v_pk_mul_f32 v[156:157], v[118:119], v[118:119]
	v_lshlrev_b64 v[92:93], 13, v[92:93]
	v_add_f32_e32 v157, v157, v162
	v_add_f32_e32 v156, v156, v157
	s_nop 1
	v_mov_b32_dpp v157, v156 row_shl:4 row_mask:0xf bank_mask:0x5
	v_mov_b32_dpp v157, v156 row_shr:4 row_mask:0xf bank_mask:0xa
	v_ashrrev_i32_e32 v95, 31, v94
	v_lshl_add_u64 v[98:99], v[128:129], 0, v[96:97]
	v_lshl_add_u64 v[108:109], v[130:131], 0, v[96:97]
	v_lshl_add_u64 v[146:147], v[92:93], 0, v[94:95]
	global_load_dwordx4 v[92:95], v[98:99], off offset:16
	global_load_dwordx4 v[104:107], v[98:99], off
	s_nop 0
	global_load_dwordx4 v[96:99], v[108:109], off offset:16
	s_nop 0
	global_load_dwordx4 v[108:111], v[108:109], off
	s_waitcnt lgkmcnt(0)
	v_add_f32_e32 v156, v156, v157
	s_nop 1
	v_mov_b32_dpp v157, v156 quad_perm:[2,3,0,1] row_mask:0xf bank_mask:0xf
	s_movk_i32 s1, 0x180
	s_waitcnt lgkmcnt(0)
	v_add_f32_e32 v156, v156, v157
	s_nop 1
	v_mov_b32_dpp v157, v156 quad_perm:[1,0,3,2] row_mask:0xf bank_mask:0xf
	s_waitcnt lgkmcnt(0)
	v_add_f32_e32 v156, v156, v157
	v_fmamk_f32 v156, v156, 0x3c000000, v189
	v_cmp_gt_f32_e32 vcc, s33, v156
	v_mul_f32_e32 v157, 0x4b800000, v156
	s_nop 0
	v_cndmask_b32_e32 v156, v156, v157, vcc
	v_rsq_f32_e32 v156, v156
	s_nop 0
	v_mul_f32_e32 v157, 0x45800000, v156
	v_cndmask_b32_e32 v156, v156, v157, vcc
	v_mul_f32_e32 v156, 0x3dd53b94, v156
	v_mul_f32_e32 v141, v156, v141
	v_mul_f32_e32 v157, v0, v141
	v_mul_f32_e32 v141, v156, v143
	v_mul_f32_e32 v143, v1, v141
	v_mul_f32_e32 v141, v156, v145
	v_mul_f32_e32 v116, v156, v116
	v_mul_f32_e32 v145, v2, v141
	v_mul_f32_e32 v141, v156, v155
	v_mul_f32_e32 v165, v11, v116
	v_mul_f32_e32 v116, v156, v123
	v_mul_f32_e32 v155, v3, v141
	v_mul_f32_e32 v141, v156, v158
	v_mul_f32_e32 v166, v12, v116
	v_mul_f32_e32 v116, v156, v122
	v_mul_f32_e32 v158, v4, v141
	v_mul_f32_e32 v141, v156, v159
	v_mul_f32_e32 v167, v13, v116
	v_mul_f32_e32 v116, v156, v119
	v_mul_f32_e32 v159, v5, v141
	v_mul_f32_e32 v141, v156, v160
	v_mul_f32_e32 v117, v156, v117
	v_mul_f32_e32 v168, v14, v116
	v_mul_f32_e32 v116, v156, v118
	v_mul_f32_e32 v160, v6, v141
	v_mul_f32_e32 v141, v156, v161
	v_mul_f32_e32 v121, v156, v121
	v_mul_f32_e32 v120, v156, v120
	v_mul_f32_e32 v164, v10, v117
	v_mul_f32_e32 v156, v15, v116
	v_mov_b64_e32 v[116:117], s[70:71]
	v_mad_u64_u32 v[116:117], s[2:3], v146, s1, v[116:117]
	v_mul_f32_e32 v161, v7, v141
	v_mad_i32_i24 v117, v147, s1, v117
	v_mov_b32_e32 v141, v177
	v_lshl_add_u64 v[122:123], v[116:117], 0, v[140:141]
	v_cvt_pk_bf16_f32 v118, v157, v143
	v_cvt_pk_bf16_f32 v119, v145, v155
	v_mul_f32_e32 v162, v8, v121
	v_mul_f32_e32 v163, v9, v120
	v_cvt_pk_bf16_f32 v120, v158, v159
	v_cvt_pk_bf16_f32 v121, v160, v161
	global_store_dwordx4 v[122:123], v[118:121], off
	s_waitcnt vmcnt(11)
	v_lshlrev_b32_e32 v157, 16, v114
	v_mov_b32_e32 v143, v177
	v_cvt_pk_bf16_f32 v118, v162, v163
	v_cvt_pk_bf16_f32 v119, v164, v165
	v_cvt_pk_bf16_f32 v120, v166, v167
	v_cvt_pk_bf16_f32 v121, v168, v156
	global_store_dwordx4 v[122:123], v[118:121], off offset:16
	v_and_b32_e32 v156, 0xffff0000, v114
	v_pk_mul_f32 v[158:159], v[156:157], v[156:157]
	v_lshlrev_b32_e32 v118, 16, v112
	v_and_b32_e32 v119, 0xffff0000, v112
	v_pk_mul_f32 v[120:121], v[118:119], v[118:119]
	v_and_b32_e32 v112, 0xffff0000, v113
	v_lshlrev_b32_e32 v113, 16, v113
	v_pk_mul_f32 v[122:123], v[112:113], v[112:113]
	v_add_f32_e32 v120, v120, v121
	v_add_f32_e32 v120, v123, v120
	v_add_f32_e32 v120, v122, v120
	v_and_b32_e32 v114, 0xffff0000, v115
	v_lshlrev_b32_e32 v115, 16, v115
	v_add_f32_e32 v120, v159, v120
	v_pk_mul_f32 v[160:161], v[114:115], v[114:115]
	v_add_f32_e32 v120, v158, v120
	v_add_f32_e32 v120, v161, v120
	v_add_f32_e32 v120, v160, v120
	s_nop 1
	v_mov_b32_dpp v121, v120 row_shl:4 row_mask:0xf bank_mask:0x5
	v_mov_b32_dpp v121, v120 row_shr:4 row_mask:0xf bank_mask:0xa
	v_lshl_add_u64 v[116:117], v[116:117], 0, v[142:143]
	v_mov_b32_e32 v145, v177
	s_waitcnt lgkmcnt(0)
	v_add_f32_e32 v120, v120, v121
	s_nop 1
	v_mov_b32_dpp v121, v120 quad_perm:[2,3,0,1] row_mask:0xf bank_mask:0xf
	s_waitcnt lgkmcnt(0)
	v_add_f32_e32 v120, v120, v121
	s_nop 1
	v_mov_b32_dpp v121, v120 quad_perm:[1,0,3,2] row_mask:0xf bank_mask:0xf
	s_waitcnt lgkmcnt(0)
	v_add_f32_e32 v120, v120, v121
	v_fmamk_f32 v120, v120, 0x3c800000, v189
	v_cmp_gt_f32_e32 vcc, s33, v120
	v_mul_f32_e32 v121, 0x4b800000, v120
	s_nop 0
	v_cndmask_b32_e32 v120, v120, v121, vcc
	v_rsq_f32_e32 v120, v120
	s_nop 0
	v_mul_f32_e32 v121, 0x45800000, v120
	v_cndmask_b32_e32 v120, v120, v121, vcc
	v_mul_f32_e32 v120, 0x3dd53b94, v120
	v_mul_f32_e32 v118, v120, v118
	v_mul_f32_e32 v118, v48, v118
	s_nop 1
	v_mov_b32_dpp v121, v118 row_shl:4 row_mask:0xf bank_mask:0x5
	v_mov_b32_dpp v121, v118 row_shr:4 row_mask:0xf bank_mask:0xa
	v_mul_f32_e32 v113, v120, v113
	v_mul_f32_e32 v113, v50, v113
	v_mul_f32_e32 v112, v120, v112
	v_mul_f32_e32 v112, v51, v112
	s_waitcnt vmcnt(2) lgkmcnt(0)
	v_mul_f32_e32 v121, v108, v121
	v_cndmask_b32_e64 v121, v121, -v121, s[40:41]
	v_fmac_f32_e32 v121, v104, v118
	v_mul_f32_e32 v118, v120, v119
	v_mul_f32_e32 v118, v49, v118
	s_nop 1
	v_mov_b32_dpp v119, v118 row_shl:4 row_mask:0xf bank_mask:0x5
	v_mov_b32_dpp v119, v118 row_shr:4 row_mask:0xf bank_mask:0xa
	s_waitcnt lgkmcnt(0)
	v_mul_f32_e32 v119, v109, v119
	v_cndmask_b32_e64 v119, v119, -v119, s[40:41]
	v_fmac_f32_e32 v119, v105, v118
	s_nop 1
	v_mov_b32_dpp v118, v113 row_shl:4 row_mask:0xf bank_mask:0x5
	v_mov_b32_dpp v118, v113 row_shr:4 row_mask:0xf bank_mask:0xa
	s_waitcnt lgkmcnt(0)
	v_mul_f32_e32 v118, v110, v118
	v_cndmask_b32_e64 v118, v118, -v118, s[40:41]
	v_fmac_f32_e32 v118, v106, v113
	s_nop 1
	v_mov_b32_dpp v113, v112 row_shl:4 row_mask:0xf bank_mask:0x5
	v_mov_b32_dpp v113, v112 row_shr:4 row_mask:0xf bank_mask:0xa
	s_waitcnt lgkmcnt(0)
	v_mul_f32_e32 v113, v111, v113
	v_cndmask_b32_e64 v113, v113, -v113, s[40:41]
	v_fmac_f32_e32 v113, v107, v112
	v_mul_f32_e32 v112, v120, v157
	v_mul_f32_e32 v112, v52, v112
	s_nop 1
	v_mov_b32_dpp v122, v112 row_shl:4 row_mask:0xf bank_mask:0x5
	v_mov_b32_dpp v122, v112 row_shr:4 row_mask:0xf bank_mask:0xa
	s_waitcnt lgkmcnt(0)
	v_mul_f32_e32 v122, v96, v122
	v_cndmask_b32_e64 v122, v122, -v122, s[40:41]
	v_fmac_f32_e32 v122, v92, v112
	v_mul_f32_e32 v112, v120, v156
	v_mul_f32_e32 v112, v53, v112
	s_nop 1
	v_mov_b32_dpp v123, v112 row_shl:4 row_mask:0xf bank_mask:0x5
	v_mov_b32_dpp v123, v112 row_shr:4 row_mask:0xf bank_mask:0xa
	s_waitcnt lgkmcnt(0)
	v_mul_f32_e32 v123, v97, v123
	v_cndmask_b32_e64 v123, v123, -v123, s[40:41]
	v_fmac_f32_e32 v123, v93, v112
	v_mul_f32_e32 v112, v120, v115
	v_mul_f32_e32 v112, v54, v112
	s_nop 1
	v_mov_b32_dpp v115, v112 row_shl:4 row_mask:0xf bank_mask:0x5
	v_mov_b32_dpp v115, v112 row_shr:4 row_mask:0xf bank_mask:0xa
	s_waitcnt lgkmcnt(0)
	v_mul_f32_e32 v115, v98, v115
	v_cndmask_b32_e64 v115, v115, -v115, s[40:41]
	v_fmac_f32_e32 v115, v94, v112
	v_mul_f32_e32 v112, v120, v114
	v_mul_f32_e32 v112, v55, v112
	s_nop 1
	v_mov_b32_dpp v114, v112 row_shl:4 row_mask:0xf bank_mask:0x5
	v_mov_b32_dpp v114, v112 row_shr:4 row_mask:0xf bank_mask:0xa
	s_waitcnt lgkmcnt(0)
	v_mul_f32_e32 v114, v99, v114
	v_cndmask_b32_e64 v120, v114, -v114, s[40:41]
	v_fmac_f32_e32 v120, v95, v112
	v_cvt_pk_bf16_f32 v112, v121, v119
	v_cvt_pk_bf16_f32 v113, v118, v113
	v_cvt_pk_bf16_f32 v114, v122, v123
	v_cvt_pk_bf16_f32 v115, v115, v120
	global_store_dwordx4 v[116:117], v[112:115], off offset:256
	v_and_b32_e32 v118, 0xffff0000, v102
	v_lshlrev_b32_e32 v119, 16, v102
	v_lshlrev_b32_e32 v112, 16, v100
	v_and_b32_e32 v113, 0xffff0000, v100
	v_pk_mul_f32 v[114:115], v[112:113], v[112:113]
	v_and_b32_e32 v100, 0xffff0000, v101
	v_lshlrev_b32_e32 v101, 16, v101
	v_pk_mul_f32 v[116:117], v[100:101], v[100:101]
	v_add_f32_e32 v114, v114, v115
	v_add_f32_e32 v114, v117, v114
	v_pk_mul_f32 v[120:121], v[118:119], v[118:119]
	v_add_f32_e32 v114, v116, v114
	v_and_b32_e32 v102, 0xffff0000, v103
	v_lshlrev_b32_e32 v103, 16, v103
	v_add_f32_e32 v114, v121, v114
	v_pk_mul_f32 v[122:123], v[102:103], v[102:103]
	v_add_f32_e32 v114, v120, v114
	v_add_f32_e32 v114, v123, v114
	v_add_f32_e32 v114, v122, v114
	s_nop 1
	v_mov_b32_dpp v115, v114 row_shl:4 row_mask:0xf bank_mask:0x5
	v_mov_b32_dpp v115, v114 row_shr:4 row_mask:0xf bank_mask:0xa
	s_waitcnt lgkmcnt(0)
	v_add_f32_e32 v114, v114, v115
	s_nop 1
	v_mov_b32_dpp v115, v114 quad_perm:[2,3,0,1] row_mask:0xf bank_mask:0xf
	s_waitcnt lgkmcnt(0)
	v_add_f32_e32 v114, v114, v115
	s_nop 1
	v_mov_b32_dpp v115, v114 quad_perm:[1,0,3,2] row_mask:0xf bank_mask:0xf
	s_waitcnt lgkmcnt(0)
	v_add_f32_e32 v114, v114, v115
	v_fmamk_f32 v114, v114, 0x3c800000, v189
	v_cmp_gt_f32_e32 vcc, s33, v114
	v_mul_f32_e32 v115, 0x4b800000, v114
	s_nop 0
	v_cndmask_b32_e32 v114, v114, v115, vcc
	v_rsq_f32_e32 v114, v114
	s_nop 0
	v_mul_f32_e32 v115, 0x45800000, v114
	v_cndmask_b32_e32 v114, v114, v115, vcc
	v_mul_f32_e32 v112, v114, v112
	v_mul_f32_e32 v112, v40, v112
	s_nop 1
	v_mov_b32_dpp v115, v112 row_shl:4 row_mask:0xf bank_mask:0x5
	v_mov_b32_dpp v115, v112 row_shr:4 row_mask:0xf bank_mask:0xa
	v_mul_f32_e32 v101, v114, v101
	v_mul_f32_e32 v101, v42, v101
	v_mul_f32_e32 v100, v114, v100
	v_mul_f32_e32 v100, v43, v100
	s_waitcnt lgkmcnt(0)
	v_mul_f32_e32 v108, v108, v115
	v_cndmask_b32_e64 v108, v108, -v108, s[40:41]
	v_fmac_f32_e32 v108, v104, v112
	v_mul_f32_e32 v104, v114, v113
	v_mul_f32_e32 v104, v41, v104
	s_nop 1
	v_mov_b32_dpp v112, v104 row_shl:4 row_mask:0xf bank_mask:0x5
	v_mov_b32_dpp v112, v104 row_shr:4 row_mask:0xf bank_mask:0xa
	s_waitcnt lgkmcnt(0)
	v_mul_f32_e32 v109, v109, v112
	v_cndmask_b32_e64 v109, v109, -v109, s[40:41]
	v_fmac_f32_e32 v109, v105, v104
	s_nop 1
	v_mov_b32_dpp v104, v101 row_shl:4 row_mask:0xf bank_mask:0x5
	v_mov_b32_dpp v104, v101 row_shr:4 row_mask:0xf bank_mask:0xa
	s_waitcnt lgkmcnt(0)
	v_mul_f32_e32 v104, v110, v104
	v_cndmask_b32_e64 v104, v104, -v104, s[40:41]
	v_fmac_f32_e32 v104, v106, v101
	s_nop 1
	v_mov_b32_dpp v101, v100 row_shl:4 row_mask:0xf bank_mask:0x5
	v_mov_b32_dpp v101, v100 row_shr:4 row_mask:0xf bank_mask:0xa
	s_waitcnt lgkmcnt(0)
	v_mul_f32_e32 v101, v111, v101
	v_cndmask_b32_e64 v101, v101, -v101, s[40:41]
	v_fmac_f32_e32 v101, v107, v100
	v_mul_f32_e32 v100, v114, v119
	v_mul_f32_e32 v100, v44, v100
	s_nop 1
	v_mov_b32_dpp v105, v100 row_shl:4 row_mask:0xf bank_mask:0x5
	v_mov_b32_dpp v105, v100 row_shr:4 row_mask:0xf bank_mask:0xa
	s_waitcnt lgkmcnt(0)
	v_mul_f32_e32 v96, v96, v105
	v_cndmask_b32_e64 v96, v96, -v96, s[40:41]
	v_fmac_f32_e32 v96, v92, v100
	v_mul_f32_e32 v92, v114, v118
	v_mul_f32_e32 v92, v45, v92
	s_nop 1
	v_mov_b32_dpp v100, v92 row_shl:4 row_mask:0xf bank_mask:0x5
	v_mov_b32_dpp v100, v92 row_shr:4 row_mask:0xf bank_mask:0xa
	s_waitcnt lgkmcnt(0)
	v_mul_f32_e32 v97, v97, v100
	v_cndmask_b32_e64 v97, v97, -v97, s[40:41]
	v_fmac_f32_e32 v97, v93, v92
	v_mul_f32_e32 v92, v114, v103
	v_mul_f32_e32 v92, v46, v92
	s_nop 1
	v_mov_b32_dpp v93, v92 row_shl:4 row_mask:0xf bank_mask:0x5
	v_mov_b32_dpp v93, v92 row_shr:4 row_mask:0xf bank_mask:0xa
	v_lshlrev_b32_e32 v100, 16, v85
	v_and_b32_e32 v103, 0xffff0000, v85
	v_and_b32_e32 v85, 0xffff0000, v86
	s_waitcnt lgkmcnt(0)
	v_mul_f32_e32 v93, v98, v93
	v_cndmask_b32_e64 v98, v93, -v93, s[40:41]
	v_fmac_f32_e32 v98, v94, v92
	v_mul_f32_e32 v92, v114, v102
	v_mul_f32_e32 v92, v47, v92
	s_nop 1
	v_mov_b32_dpp v93, v92 row_shl:4 row_mask:0xf bank_mask:0x5
	v_mov_b32_dpp v93, v92 row_shr:4 row_mask:0xf bank_mask:0xa
	v_and_b32_e32 v102, 0xffff0000, v81
	s_waitcnt lgkmcnt(0)
	v_mul_f32_e32 v93, v99, v93
	v_cndmask_b32_e64 v99, v93, -v93, s[40:41]
	v_fmac_f32_e32 v99, v95, v92
	v_cvt_pk_bf16_f32 v92, v108, v109
	v_cvt_pk_bf16_f32 v93, v104, v101
	v_cvt_pk_bf16_f32 v94, v96, v97
	v_mov_b64_e32 v[96:97], s[68:69]
	v_mad_u64_u32 v[96:97], s[2:3], v146, s1, v[96:97]
	v_mad_i32_i24 v97, v147, s1, v97
	v_lshl_add_u64 v[96:97], v[96:97], 0, v[142:143]
	s_mov_b32 s1, 0x2b000000
	v_add_co_u32_e32 v96, vcc, s1, v96
	v_cvt_pk_bf16_f32 v95, v98, v99
	v_lshlrev_b32_e32 v101, 16, v81
	s_nop 0
	v_addc_co_u32_e32 v97, vcc, 0, v97, vcc
	global_store_dwordx4 v[96:97], v[92:95], off offset:256
	v_lshlrev_b32_e32 v96, 16, v89
	v_and_b32_e32 v97, 0xffff0000, v89
	v_and_b32_e32 v95, 0xffff0000, v88
	v_lshlrev_b32_e32 v94, 16, v88
	v_mul_f32_e32 v98, v95, v95
	v_fmac_f32_e32 v98, v94, v94
	v_fmac_f32_e32 v98, v96, v96
	v_and_b32_e32 v88, 0xffff0000, v90
	v_lshlrev_b32_e32 v89, 16, v90
	v_fmac_f32_e32 v98, v97, v97
	v_pk_mul_f32 v[92:93], v[88:89], v[88:89]
	v_and_b32_e32 v81, 0xffff0000, v82
	v_add_f32_e32 v90, v93, v98
	v_add_f32_e32 v98, v92, v90
	v_and_b32_e32 v90, 0xffff0000, v91
	v_lshlrev_b32_e32 v91, 16, v91
	v_pk_mul_f32 v[92:93], v[90:91], v[90:91]
	v_and_b32_e32 v99, 0xffff0000, v84
	v_add_f32_e32 v93, v93, v98
	v_add_f32_e32 v92, v92, v93
	ds_bpermute_b32 v93, v152, v92
	s_waitcnt lgkmcnt(0)
	v_add_f32_e32 v92, v92, v93
	ds_bpermute_b32 v93, v153, v92
	s_waitcnt lgkmcnt(0)
	v_add_f32_e32 v92, v92, v93
	s_nop 1
	v_mov_b32_dpp v93, v92 row_ror:8 row_mask:0xf bank_mask:0xf
	s_waitcnt lgkmcnt(0)
	v_add_f32_e32 v92, v92, v93
	s_nop 1
	v_mov_b32_dpp v93, v92 row_shl:4 row_mask:0xf bank_mask:0x5
	v_mov_b32_dpp v93, v92 row_shr:4 row_mask:0xf bank_mask:0xa
	s_waitcnt lgkmcnt(0)
	v_add_f32_e32 v92, v92, v93
	s_nop 1
	v_mov_b32_dpp v93, v92 quad_perm:[2,3,0,1] row_mask:0xf bank_mask:0xf
	s_waitcnt lgkmcnt(0)
	v_add_f32_e32 v92, v92, v93
	s_nop 1
	v_mov_b32_dpp v93, v92 quad_perm:[1,0,3,2] row_mask:0xf bank_mask:0xf
	s_waitcnt lgkmcnt(0)
	v_add_f32_e32 v92, v92, v93
	v_fmamk_f32 v92, v92, 0x3b000000, v189
	v_cmp_gt_f32_e32 vcc, s33, v92
	v_mul_f32_e32 v93, 0x4b800000, v92
	s_nop 0
	v_cndmask_b32_e32 v92, v92, v93, vcc
	v_rsq_f32_e32 v92, v92
	s_nop 0
	v_mul_f32_e32 v93, 0x45800000, v92
	v_cndmask_b32_e32 v92, v92, v93, vcc
	v_mul_f32_e32 v93, v92, v94
	v_mul_f32_e32 v94, v92, v95
	v_mul_f32_e32 v95, v92, v96
	v_mul_f32_e32 v96, v92, v97
	v_mul_f32_e32 v97, v92, v89
	v_mul_f32_e32 v98, v92, v88
	v_mul_f32_e32 v91, v92, v91
	v_mul_f32_e32 v92, v92, v90
	v_cvt_pk_bf16_f32 v88, v93, v94
	v_cvt_pk_bf16_f32 v89, v95, v96
	v_cvt_pk_bf16_f32 v90, v97, v98
	v_cvt_pk_bf16_f32 v91, v91, v92
	v_lshlrev_b64 v[92:93], 10, v[124:125]
	v_lshlrev_b32_e32 v96, 16, v80
	v_lshlrev_b32_e32 v97, 16, v84
	v_lshl_add_u64 v[92:93], v[126:127], 0, v[92:93]
	v_and_b32_e32 v98, 0xffff0000, v80
	v_lshlrev_b32_e32 v80, 16, v82
	v_mul_f32_e32 v82, v96, v97
	global_store_dwordx4 v[92:93], v[88:91], off
	v_and_b32_e32 v92, 0xffff0000, v57
	v_and_b32_e32 v93, 0xffff0000, v60
	v_lshlrev_b32_e32 v88, 16, v56
	v_and_b32_e32 v90, 0xffff0000, v56
	v_lshlrev_b32_e32 v91, 16, v57
	v_lshlrev_b32_e32 v89, 16, v60
	v_lshlrev_b32_e32 v94, 16, v61
	v_and_b32_e32 v95, 0xffff0000, v61
	v_lshlrev_b32_e32 v84, 16, v86
	v_lshlrev_b32_e32 v56, 16, v87
	v_lshlrev_b32_e32 v60, 16, v83
	v_and_b32_e32 v61, 0xffff0000, v83
	v_and_b32_e32 v57, 0xffff0000, v87
	v_fma_f32 v96, v16, v82, v24
	v_lshlrev_b32_e32 v83, 16, v76
	v_lshlrev_b32_e32 v82, 16, v68
	v_lshlrev_b32_e32 v87, 16, v72
	v_lshlrev_b32_e32 v86, 16, v64
	v_pk_mul_f32 v[82:83], v[82:83], v[86:87]
	v_pk_mul_f32 v[80:81], v[84:85], v[80:81]
	v_pk_mul_f32 v[82:83], v[138:139], v[82:83]
	v_pk_fma_f32 v[80:81], v[20:21], v[80:81], v[28:29]
	v_add_f32_e32 v82, v82, v96
	v_add_f32_e32 v82, v82, v83
	v_mul_f32_e32 v83, 0xbfb8aa3b, v89
	v_exp_f32_e32 v83, v83
	v_mul_f32_e32 v82, v82, v88
	v_pk_mul_f32 v[56:57], v[56:57], v[60:61]
	v_add_f32_e32 v83, 1.0, v83
	v_div_scale_f32 v86, s[2:3], v83, v83, v89
	v_rcp_f32_e32 v87, v86
	v_pk_fma_f32 v[56:57], v[22:23], v[56:57], v[30:31]
	v_fma_f32 v88, -v86, v87, 1.0
	v_fmac_f32_e32 v87, v88, v87
	v_div_scale_f32 v88, vcc, v89, v83, v89
	v_mul_f32_e32 v96, v88, v87
	v_fma_f32 v97, -v86, v96, v88
	v_fmac_f32_e32 v96, v97, v87
	v_fma_f32 v86, -v86, v96, v88
	v_div_fmas_f32 v86, v86, v87, v96
	v_div_fixup_f32 v83, v86, v83, v89
	v_and_b32_e32 v86, 0xffff0000, v68
	v_mul_f32_e32 v68, 0xbfb8aa3b, v93
	v_exp_f32_e32 v68, v68
	v_and_b32_e32 v89, 0xffff0000, v72
	v_and_b32_e32 v87, 0xffff0000, v76
	v_and_b32_e32 v88, 0xffff0000, v64
	v_add_f32_e32 v68, 1.0, v68
	v_div_scale_f32 v72, s[2:3], v68, v68, v93
	v_rcp_f32_e32 v76, v72
	v_mul_f32_e32 v82, v83, v82
	v_mul_f32_e32 v83, v98, v99
	v_pk_mul_f32 v[86:87], v[86:87], v[88:89]
	v_fma_f32 v83, v17, v83, v25
	v_pk_mul_f32 v[86:87], v[32:33], v[86:87]
	v_lshlrev_b32_e32 v89, 16, v73
	v_add_f32_e32 v64, v86, v83
	v_fma_f32 v83, -v72, v76, 1.0
	v_fmac_f32_e32 v76, v83, v76
	v_div_scale_f32 v83, vcc, v93, v68, v93
	v_mul_f32_e32 v86, v83, v76
	v_add_f32_e32 v64, v64, v87
	v_fma_f32 v87, -v72, v86, v83
	v_fmac_f32_e32 v86, v87, v76
	v_fma_f32 v72, -v72, v86, v83
	v_div_fmas_f32 v72, v72, v76, v86
	v_div_fixup_f32 v68, v72, v68, v93
	v_mul_f32_e32 v72, 0xbfb8aa3b, v94
	v_exp_f32_e32 v72, v72
	v_mul_f32_e32 v64, v64, v90
	v_lshlrev_b32_e32 v87, 16, v77
	v_lshlrev_b32_e32 v86, 16, v69
	v_lshlrev_b32_e32 v88, 16, v65
	v_mul_f32_e32 v68, v68, v64
	v_mul_f32_e32 v64, v101, v100
	v_pk_mul_f32 v[86:87], v[86:87], v[88:89]
	v_add_f32_e32 v72, 1.0, v72
	v_fma_f32 v64, v18, v64, v26
	v_pk_mul_f32 v[86:87], v[136:137], v[86:87]
	v_div_scale_f32 v76, s[2:3], v72, v72, v94
	v_add_f32_e32 v64, v86, v64
	v_rcp_f32_e32 v86, v76
	v_add_f32_e32 v64, v64, v87
	v_mul_f32_e32 v64, v64, v91
	v_and_b32_e32 v77, 0xffff0000, v77
	v_fma_f32 v87, -v76, v86, 1.0
	v_fmac_f32_e32 v86, v87, v86
	v_div_scale_f32 v87, vcc, v94, v72, v94
	v_mul_f32_e32 v88, v87, v86
	v_fma_f32 v89, -v76, v88, v87
	v_fmac_f32_e32 v88, v89, v86
	v_fma_f32 v76, -v76, v88, v87
	v_div_fmas_f32 v76, v76, v86, v88
	v_div_fixup_f32 v72, v76, v72, v94
	v_mul_f32_e32 v72, v72, v64
	v_mul_f32_e32 v64, v102, v103
	v_and_b32_e32 v76, 0xffff0000, v69
	v_and_b32_e32 v87, 0xffff0000, v73
	v_and_b32_e32 v86, 0xffff0000, v65
	v_fma_f32 v88, v19, v64, v27
	v_pk_mul_f32 v[64:65], v[76:77], v[86:87]
	v_and_b32_e32 v87, 0xffff0000, v74
	v_pk_mul_f32 v[64:65], v[34:35], v[64:65]
	v_mul_f32_e32 v83, v68, v68
	v_add_f32_e32 v64, v64, v88
	v_add_f32_e32 v64, v64, v65
	v_mul_f32_e32 v65, 0xbfb8aa3b, v95
	v_exp_f32_e32 v65, v65
	v_mul_f32_e32 v64, v64, v92
	v_fmac_f32_e32 v83, v82, v82
	v_fmac_f32_e32 v83, v72, v72
	v_add_f32_e32 v65, 1.0, v65
	v_div_scale_f32 v69, s[2:3], v65, v65, v95
	v_rcp_f32_e32 v73, v69
	s_nop 0
	v_fma_f32 v76, -v69, v73, 1.0
	v_fmac_f32_e32 v73, v76, v73
	v_div_scale_f32 v76, vcc, v95, v65, v95
	v_mul_f32_e32 v77, v76, v73
	v_fma_f32 v86, -v69, v77, v76
	v_fmac_f32_e32 v77, v86, v73
	v_fma_f32 v69, -v69, v77, v76
	v_div_fmas_f32 v69, v69, v73, v77
	v_div_fixup_f32 v65, v69, v65, v95
	v_mul_f32_e32 v69, v65, v64
	v_lshlrev_b32_e32 v65, 16, v78
	v_lshlrev_b32_e32 v64, 16, v70
	v_lshlrev_b32_e32 v77, 16, v74
	v_lshlrev_b32_e32 v76, 16, v66
	v_pk_mul_f32 v[64:65], v[64:65], v[76:77]
	v_and_b32_e32 v77, 0xffff0000, v78
	v_and_b32_e32 v76, 0xffff0000, v70
	v_and_b32_e32 v86, 0xffff0000, v66
	v_pk_mul_f32 v[76:77], v[76:77], v[86:87]
	v_and_b32_e32 v87, 0xffff0000, v58
	v_lshlrev_b32_e32 v86, 16, v58
	v_and_b32_e32 v58, 0xffff0000, v62
	v_lshlrev_b32_e32 v62, 16, v62
	v_mul_f32_e32 v66, 0xbfb8aa3b, v62
	v_exp_f32_e32 v88, v66
	v_mul_f32_e32 v66, 0xbfb8aa3b, v58
	v_exp_f32_e32 v89, v66
	v_pk_mul_f32 v[64:65], v[134:135], v[64:65]
	v_pk_mul_f32 v[76:77], v[36:37], v[76:77]
	v_mov_b32_e32 v84, v64
	v_mov_b32_e32 v85, v76
	v_pk_add_f32 v[80:81], v[84:85], v[80:81]
	v_mov_b32_e32 v76, v65
	v_pk_add_f32 v[64:65], v[80:81], v[76:77]
	v_pk_add_f32 v[76:77], v[88:89], 1.0 op_sel_hi:[1,0]
	v_pk_mul_f32 v[64:65], v[64:65], v[86:87]
	v_div_scale_f32 v66, s[2:3], v77, v77, v58
	v_rcp_f32_e32 v70, v66
	v_fmac_f32_e32 v83, v69, v69
	v_lshlrev_b32_e32 v80, 16, v67
	v_lshlrev_b32_e32 v81, 16, v75
	v_fma_f32 v73, -v66, v70, 1.0
	v_fmac_f32_e32 v70, v73, v70
	v_div_scale_f32 v73, vcc, v58, v77, v58
	v_mul_f32_e32 v74, v73, v70
	v_fma_f32 v78, -v66, v74, v73
	v_fmac_f32_e32 v74, v78, v70
	v_fma_f32 v66, -v66, v74, v73
	v_div_fmas_f32 v66, v66, v70, v74
	v_div_fixup_f32 v77, v66, v77, v58
	v_div_scale_f32 v58, s[2:3], v76, v76, v62
	v_rcp_f32_e32 v66, v58
	v_and_b32_e32 v78, 0xffff0000, v71
	v_fma_f32 v70, -v58, v66, 1.0
	v_fmac_f32_e32 v66, v70, v66
	v_div_scale_f32 v70, vcc, v62, v76, v62
	v_mul_f32_e32 v73, v70, v66
	v_fma_f32 v74, -v58, v73, v70
	v_fmac_f32_e32 v73, v74, v66
	v_fma_f32 v58, -v58, v73, v70
	v_div_fmas_f32 v58, v58, v66, v73
	v_div_fixup_f32 v76, v58, v76, v62
	v_pk_mul_f32 v[64:65], v[76:77], v[64:65]
	v_and_b32_e32 v70, 0xffff0000, v67
	v_pk_mul_f32 v[76:77], v[64:65], v[64:65]
	v_and_b32_e32 v73, 0xffff0000, v63
	v_add_f32_e32 v58, v76, v83
	v_add_f32_e32 v62, v77, v58
	v_lshlrev_b32_e32 v77, 16, v79
	v_lshlrev_b32_e32 v76, 16, v71
	v_and_b32_e32 v79, 0xffff0000, v79
	v_and_b32_e32 v71, 0xffff0000, v75
	v_lshlrev_b32_e32 v63, 16, v63
	v_pk_mul_f32 v[66:67], v[78:79], v[70:71]
	v_and_b32_e32 v71, 0xffff0000, v59
	v_lshlrev_b32_e32 v70, 16, v59
	v_mul_f32_e32 v58, 0xbfb8aa3b, v63
	v_mul_f32_e32 v59, 0xbfb8aa3b, v73
	v_exp_f32_e32 v58, v58
	v_exp_f32_e32 v59, v59
	v_pk_mul_f32 v[76:77], v[76:77], v[80:81]
	v_pk_mul_f32 v[66:67], v[38:39], v[66:67]
	v_pk_mul_f32 v[76:77], v[132:133], v[76:77]
	v_mov_b32_e32 v61, v66
	v_mov_b32_e32 v60, v76
	v_pk_add_f32 v[58:59], v[58:59], 1.0 op_sel_hi:[1,0]
	v_pk_add_f32 v[56:57], v[60:61], v[56:57]
	v_div_scale_f32 v60, s[2:3], v59, v59, v73
	v_rcp_f32_e32 v61, v60
	v_mov_b32_e32 v66, v77
	v_pk_add_f32 v[56:57], v[56:57], v[66:67]
	v_fma_f32 v66, -v60, v61, 1.0
	v_fmac_f32_e32 v61, v66, v61
	v_div_scale_f32 v66, vcc, v73, v59, v73
	v_mul_f32_e32 v67, v66, v61
	v_pk_mul_f32 v[56:57], v[56:57], v[70:71]
	v_fma_f32 v70, -v60, v67, v66
	v_fmac_f32_e32 v67, v70, v61
	v_fma_f32 v60, -v60, v67, v66
	v_div_fmas_f32 v60, v60, v61, v67
	v_div_fixup_f32 v59, v60, v59, v73
	v_div_scale_f32 v60, s[2:3], v58, v58, v63
	v_rcp_f32_e32 v61, v60
	s_nop 0
	v_fma_f32 v66, -v60, v61, 1.0
	v_fmac_f32_e32 v61, v66, v61
	v_div_scale_f32 v66, vcc, v63, v58, v63
	v_mul_f32_e32 v67, v66, v61
	v_fma_f32 v70, -v60, v67, v66
	v_fmac_f32_e32 v67, v70, v61
	v_fma_f32 v60, -v60, v67, v66
	v_div_fmas_f32 v60, v60, v61, v67
	v_div_fixup_f32 v58, v60, v58, v63
	v_pk_mul_f32 v[56:57], v[58:59], v[56:57]
	s_nop 0
	v_pk_mul_f32 v[58:59], v[56:57], v[56:57]
	s_nop 0
	v_add_f32_e32 v58, v58, v62
	v_add_f32_e32 v58, v59, v58
	ds_bpermute_b32 v59, v152, v58
	s_waitcnt lgkmcnt(0)
	v_add_f32_e32 v58, v58, v59
	ds_bpermute_b32 v59, v153, v58
	s_waitcnt lgkmcnt(0)
	v_add_f32_e32 v58, v58, v59
	s_nop 1
	v_mov_b32_dpp v59, v58 row_ror:8 row_mask:0xf bank_mask:0xf
	s_waitcnt lgkmcnt(0)
	v_add_f32_e32 v58, v58, v59
	s_nop 1
	v_mov_b32_dpp v59, v58 row_shl:4 row_mask:0xf bank_mask:0x5
	v_mov_b32_dpp v59, v58 row_shr:4 row_mask:0xf bank_mask:0xa
	s_waitcnt lgkmcnt(0)
	v_add_f32_e32 v58, v58, v59
	s_nop 1
	v_mov_b32_dpp v59, v58 quad_perm:[2,3,0,1] row_mask:0xf bank_mask:0xf
	s_waitcnt lgkmcnt(0)
	v_add_f32_e32 v58, v58, v59
	s_nop 1
	v_mov_b32_dpp v59, v58 quad_perm:[1,0,3,2] row_mask:0xf bank_mask:0xf
	s_waitcnt lgkmcnt(0)
	v_add_f32_e32 v58, v58, v59
	v_fmamk_f32 v58, v58, 0x3b000000, v189
	v_cmp_gt_f32_e32 vcc, s33, v58
	v_mul_f32_e32 v59, 0x4b800000, v58
	s_nop 0
	v_cndmask_b32_e32 v58, v58, v59, vcc
	v_rsq_f32_e32 v58, v58
	s_nop 0
	v_mul_f32_e32 v59, 0x45800000, v58
	v_cndmask_b32_e32 v58, v58, v59, vcc
	v_mul_f32_e32 v60, v68, v58
	v_mul_f32_e32 v61, v72, v58
	v_mul_f32_e32 v59, v82, v58
	v_mul_f32_e32 v62, v69, v58
	v_mul_f32_e32 v63, v64, v58
	v_mul_f32_e32 v64, v65, v58
	v_mul_f32_e32 v65, v56, v58
	v_mul_f32_e32 v66, v57, v58
	v_cvt_pk_bf16_f32 v56, v59, v60
	v_cvt_pk_bf16_f32 v57, v61, v62
	v_lshlrev_b64 v[60:61], 12, v[124:125]
	v_lshl_add_u64 v[60:61], s[68:69], 0, v[60:61]
	v_lshl_add_u64 v[60:61], v[60:61], 0, v[144:145]
	v_add_co_u32_e32 v60, vcc, 0xd800000, v60
	v_add_u32_e32 v124, s48, v124
	s_nop 0
	v_addc_co_u32_e32 v61, vcc, 0, v61, vcc
	v_cmp_lt_i32_e32 vcc, s15, v124
	s_or_b64 s[44:45], vcc, s[44:45]
	v_cvt_pk_bf16_f32 v58, v63, v64
	v_cvt_pk_bf16_f32 v59, v65, v66
	global_store_dwordx4 v[60:61], v[56:59], off offset:3072
	s_andn2_b64 exec, exec, s[44:45]
	s_cbranch_execz .LBB0_262

.LBB0_262:
	s_nop 0
	s_nop 0
	s_nop 0
	s_nop 0
	s_nop 0
	s_or_b64 exec, exec, s[38:39]
	v_mov_b32_e32 v0, v177
	s_waitcnt vmcnt(0)
	s_barrier
	v_readlane_b32 s1, v253, 4
	v_mbcnt_lo_u32_b32 v0, -1, v0
	v_mbcnt_hi_u32_b32 v0, -1, v0
	v_cmp_eq_u32_e32 vcc, s1, v0
	s_and_saveexec_b64 s[38:39], vcc
	s_cbranch_execz .LBB0_314
	v_readlane_b32 s1, v255, 12
	s_waitcnt vmcnt(0) expcnt(0) lgkmcnt(0)
	s_nop 0
	v_mov_b32_e32 v0, s1
	ds_read_b32 v2, v0
	v_readlane_b32 s1, v255, 13
	s_waitcnt lgkmcnt(0)
	v_cmp_ne_u32_e32 vcc, 0, v2
	v_mov_b32_e32 v0, s1
	ds_read_b32 v0, v0
	s_cbranch_vccnz .LBB0_278
	s_mov_b32 s1, 1
	s_branch .LBB0_266
